# v109 + ph_gu K-loop: 12 LDS-DMA loads whose address is SGPR pair + zero-extended lane offset use the saddr form (64-bit VALU adds dropped)
# speedup vs baseline: 1.0039x; 1.0039x over previous
; #define PG8_STAGE(bufoff, gbase, voff) do { _Pragma("unroll") for (int _i = 0; _i < 2; ++_i) \
;         __builtin_amdgcn_global_load_lds((const unsigned*)((const char*)(gbase) + (voff)[_i]), (LAS unsigned*)(lds + (bufoff) + ldsw + _i * 8192), 16, 0, 0); } while (0)
; #define PG8_LDA(dst, b, h) do { _Pragma("unroll") for (int m = 0; m < 4; ++m) _Pragma("unroll") for (int k = 0; k < 2; ++k) dst[m][k] = *(const LAS bf16x8*)(lds + PG8_SA(b, h) + aoff + m * 2048 + k * 1024); } while (0)
; #define PG8_LDB(dst, b, h) do { _Pragma("unroll") for (int n = 0; n < 2; ++n) _Pragma("unroll") for (int k = 0; k < 2; ++k) dst[n][k] = *(const LAS bf16x8*)(lds + PG8_SB(b, h) + boff + n * 2048 + k * 1024); } while (0)
; #define PG8_MMA(ai, bj, At, Bt) do { __builtin_amdgcn_s_setprio(1); _Pragma("unroll") for (int m = 0; m < 4; ++m) _Pragma("unroll") for (int n = 0; n < 2; ++n) _Pragma("unroll") for (int k = 0; k < 2; ++k) \
;         acc[ai][bj][m][n] = __builtin_amdgcn_mfma_f32_16x16x32_bf16(Bt[n][k], At[m][k], acc[ai][bj][m][n], 0, 0, 0); __builtin_amdgcn_s_setprio(0); } while (0)
; #define PG8_WAIT_V(n) asm volatile("s_waitcnt vmcnt(" #n ")" ::: "memory")
; #define PG8_WAIT_L(n) asm volatile("s_waitcnt lgkmcnt(" #n ")" ::: "memory")
; #define PG8_BAR __builtin_amdgcn_s_barrier()
; #define PG8_SCHED __builtin_amdgcn_sched_barrier(0)
; template <class Epi>
; DI void gemm_phase(LAS unsigned char* lds, const Gemm g, const StaticOrder& S, const Epi& E) {
;     ...
;             PG8_LDB(B0, 0, 0); PG8_LDB(B1, 0, 1); PG8_SCHED; PG8_LDA(At, 0, 0); PG8_STAGE(PG8_SA(1, 1), a1 + hstep, voffA);
;             PG8_WAIT_V(8); PG8_WAIT_L(0); PG8_BAR; PG8_MMA(0, 0, At, B0); PG8_MMA(0, 1, At, B1); PG8_BAR; PG8_SCHED;
;             PG8_LDA(At, 0, 1); PG8_STAGE(PG8_SB(0, 0), b2, voffB); PG8_STAGE(PG8_SB(0, 1), b2 + hstep, voffB); PG8_STAGE(PG8_SA(0, 0), a2, voffA);
;             PG8_WAIT_V(8); PG8_WAIT_L(0); PG8_BAR; PG8_MMA(1, 0, At, B0); PG8_MMA(1, 1, At, B1); PG8_BAR; PG8_SCHED;
.Lsp_1:
	s_add_u32 s18, s56, 0xfffc0080
	s_addc_u32 s19, s57, -1
	s_add_i32 s69, 0, 0x10000
	s_cmp_eq_u32 s68, 12
	s_cselect_b32 s61, s22, s19
	s_cselect_b32 s60, s23, s18
	v_add_u32_e32 v122, s69, v184
	s_cselect_b32 s59, s42, s49
	s_cselect_b32 s58, s43, s47
	s_add_i32 s70, 0, 0x14000
	ds_read_b128 v[102:105], v122
	ds_read_b128 v[132:135], v122 offset:1024
	ds_read_b128 v[140:143], v122 offset:2048
	ds_read_b128 v[144:147], v122 offset:3072
	v_add_u32_e32 v122, s70, v184
	ds_read_b128 v[148:151], v122
	ds_read_b128 v[166:169], v122 offset:1024
	ds_read_b128 v[170:173], v122 offset:2048
	ds_read_b128 v[174:177], v122 offset:3072
	s_add_i32 m0, s55, 0xc000
	ds_read_b128 v[178:181], v186
	ds_read_b128 v[188:191], v186 offset:1024
	ds_read_b128 v[200:203], v186 offset:2048
	ds_read_b128 v[206:209], v186 offset:3072
	ds_read_b128 v[210:213], v186 offset:4096
	ds_read_b128 v[214:217], v186 offset:5120
	ds_read_b128 v[218:221], v186 offset:6144
	ds_read_b128 v[222:225], v186 offset:7168
	global_load_lds_dwordx4 v164, s[56:57]
	s_add_i32 m0, s55, 0xe000
	s_nop 0
	global_load_lds_dwordx4 v162, s[56:57]
	s_waitcnt vmcnt(8)
	s_waitcnt lgkmcnt(0)
	s_barrier
	s_waitcnt lgkmcnt(0)
	v_mfma_f32_16x16x32_bf16 v[136:139], v[102:105], v[178:181], 0
	v_mfma_f32_16x16x32_bf16 v[128:131], v[140:143], v[178:181], 0
	v_mfma_f32_16x16x32_bf16 v[118:121], v[102:105], v[200:203], 0
	v_mfma_f32_16x16x32_bf16 v[110:113], v[140:143], v[200:203], 0
	v_mfma_f32_16x16x32_bf16 v[98:101], v[102:105], v[210:213], 0
	v_mfma_f32_16x16x32_bf16 v[90:93], v[140:143], v[210:213], 0
	v_mfma_f32_16x16x32_bf16 v[78:81], v[102:105], v[218:221], 0
	v_mfma_f32_16x16x32_bf16 v[70:73], v[140:143], v[218:221], 0
	v_mfma_f32_16x16x32_bf16 v[136:139], v[132:135], v[188:191], v[136:139]
	v_mfma_f32_16x16x32_bf16 v[128:131], v[144:147], v[188:191], v[128:131]
	v_mfma_f32_16x16x32_bf16 v[118:121], v[132:135], v[206:209], v[118:121]
	v_mfma_f32_16x16x32_bf16 v[110:113], v[144:147], v[206:209], v[110:113]
	v_mfma_f32_16x16x32_bf16 v[98:101], v[132:135], v[214:217], v[98:101]
	v_mfma_f32_16x16x32_bf16 v[90:93], v[144:147], v[214:217], v[90:93]
	v_mfma_f32_16x16x32_bf16 v[78:81], v[132:135], v[222:225], v[78:81]
	v_mfma_f32_16x16x32_bf16 v[70:73], v[144:147], v[222:225], v[70:73]
	v_mfma_f32_16x16x32_bf16 v[82:85], v[148:151], v[178:181], 0
	v_mfma_f32_16x16x32_bf16 v[122:125], v[170:173], v[178:181], 0
	v_mfma_f32_16x16x32_bf16 v[114:117], v[148:151], v[200:203], 0
	v_mfma_f32_16x16x32_bf16 v[106:109], v[170:173], v[200:203], 0
	v_mfma_f32_16x16x32_bf16 v[94:97], v[148:151], v[210:213], 0
	v_mfma_f32_16x16x32_bf16 v[86:89], v[170:173], v[210:213], 0
	v_mfma_f32_16x16x32_bf16 v[74:77], v[148:151], v[218:221], 0
	v_mfma_f32_16x16x32_bf16 v[66:69], v[170:173], v[218:221], 0
	v_mfma_f32_16x16x32_bf16 v[82:85], v[166:169], v[188:191], v[82:85]
	v_mfma_f32_16x16x32_bf16 v[122:125], v[174:177], v[188:191], v[122:125]
	v_mfma_f32_16x16x32_bf16 v[114:117], v[166:169], v[206:209], v[114:117]
	v_mfma_f32_16x16x32_bf16 v[106:109], v[174:177], v[206:209], v[106:109]
	v_mfma_f32_16x16x32_bf16 v[94:97], v[166:169], v[214:217], v[94:97]
	v_mfma_f32_16x16x32_bf16 v[86:89], v[174:177], v[214:217], v[86:89]
	v_mfma_f32_16x16x32_bf16 v[74:77], v[166:169], v[222:225], v[74:77]
	v_mfma_f32_16x16x32_bf16 v[66:69], v[174:177], v[222:225], v[66:69]
	s_barrier
	s_add_i32 s18, s69, s37
	v_lshl_add_u64 v[182:183], s[58:59], 0, v[156:157]
	s_mov_b32 m0, s18
	ds_read_b128 v[178:181], v186 offset:16384
	ds_read_b128 v[188:191], v186 offset:17408
	ds_read_b128 v[200:203], v186 offset:18432
	ds_read_b128 v[206:209], v186 offset:19456
	ds_read_b128 v[210:213], v186 offset:20480
	ds_read_b128 v[214:217], v186 offset:21504
	ds_read_b128 v[218:221], v186 offset:22528
	ds_read_b128 v[222:225], v186 offset:23552
	global_load_lds_dwordx4 v[182:183], off
	s_add_i32 m0, s18, 0x2000
	s_add_u32 s18, s58, 0x40000
	v_lshl_add_u64 v[192:193], s[58:59], 0, v[152:153]
	s_addc_u32 s19, s59, 0
	s_add_i32 s69, s70, s37
	global_load_lds_dwordx4 v[192:193], off
	s_mov_b32 m0, s69
	v_lshl_add_u64 v[204:205], s[60:61], 0, v[158:159]
	global_load_lds_dwordx4 v156, s[18:19]
	s_add_i32 m0, s69, 0x2000
	v_lshl_add_u64 v[226:227], s[60:61], 0, v[154:155]
	global_load_lds_dwordx4 v152, s[18:19]
	s_mov_b32 m0, s55
	s_nop 0
	global_load_lds_dwordx4 v[204:205], off
	s_mov_b32 m0, s63
	s_nop 0
	global_load_lds_dwordx4 v[226:227], off
	s_waitcnt vmcnt(8)
	s_waitcnt lgkmcnt(0)
	s_barrier
	s_waitcnt lgkmcnt(0)
	v_mfma_f32_16x16x32_bf16 v[62:65], v[102:105], v[178:181], 0
	v_mfma_f32_16x16x32_bf16 v[54:57], v[140:143], v[178:181], 0
	v_mfma_f32_16x16x32_bf16 v[46:49], v[102:105], v[200:203], 0
	v_mfma_f32_16x16x32_bf16 v[38:41], v[140:143], v[200:203], 0
	v_mfma_f32_16x16x32_bf16 v[30:33], v[102:105], v[210:213], 0
	v_mfma_f32_16x16x32_bf16 v[22:25], v[140:143], v[210:213], 0
	v_mfma_f32_16x16x32_bf16 v[14:17], v[102:105], v[218:221], 0
	v_mfma_f32_16x16x32_bf16 v[6:9], v[140:143], v[218:221], 0
	v_mfma_f32_16x16x32_bf16 v[62:65], v[132:135], v[188:191], v[62:65]
	v_mfma_f32_16x16x32_bf16 v[54:57], v[144:147], v[188:191], v[54:57]
	v_mfma_f32_16x16x32_bf16 v[46:49], v[132:135], v[206:209], v[46:49]
	v_mfma_f32_16x16x32_bf16 v[38:41], v[144:147], v[206:209], v[38:41]
	v_mfma_f32_16x16x32_bf16 v[30:33], v[132:135], v[214:217], v[30:33]
	v_mfma_f32_16x16x32_bf16 v[22:25], v[144:147], v[214:217], v[22:25]
	v_mfma_f32_16x16x32_bf16 v[14:17], v[132:135], v[222:225], v[14:17]
	v_mfma_f32_16x16x32_bf16 v[6:9], v[144:147], v[222:225], v[6:9]
	v_mfma_f32_16x16x32_bf16 v[58:61], v[148:151], v[178:181], 0
	v_mfma_f32_16x16x32_bf16 v[50:53], v[170:173], v[178:181], 0
	v_mfma_f32_16x16x32_bf16 v[42:45], v[148:151], v[200:203], 0
	v_mfma_f32_16x16x32_bf16 v[34:37], v[170:173], v[200:203], 0
	v_mfma_f32_16x16x32_bf16 v[26:29], v[148:151], v[210:213], 0
	v_mfma_f32_16x16x32_bf16 v[18:21], v[170:173], v[210:213], 0
	v_mfma_f32_16x16x32_bf16 v[10:13], v[148:151], v[218:221], 0
	v_mfma_f32_16x16x32_bf16 v[2:5], v[170:173], v[218:221], 0
	v_mfma_f32_16x16x32_bf16 v[58:61], v[166:169], v[188:191], v[58:61]
	v_mfma_f32_16x16x32_bf16 v[50:53], v[174:177], v[188:191], v[50:53]
	v_mfma_f32_16x16x32_bf16 v[42:45], v[166:169], v[206:209], v[42:45]
	v_mfma_f32_16x16x32_bf16 v[34:37], v[174:177], v[206:209], v[34:37]
	v_mfma_f32_16x16x32_bf16 v[26:29], v[166:169], v[214:217], v[26:29]
	v_mfma_f32_16x16x32_bf16 v[18:21], v[174:177], v[214:217], v[18:21]
	v_mfma_f32_16x16x32_bf16 v[10:13], v[166:169], v[222:225], v[10:13]
	v_mfma_f32_16x16x32_bf16 v[2:5], v[174:177], v[222:225], v[2:5]
	s_barrier
	s_branch .Lp3_gu
; #define PG8_STAGE(bufoff, gbase, voff) do { _Pragma("unroll") for (int _i = 0; _i < 2; ++_i) \
;         __builtin_amdgcn_global_load_lds((const unsigned*)((const char*)(gbase) + (voff)[_i]), (LAS unsigned*)(lds + (bufoff) + ldsw + _i * 8192), 16, 0, 0); } while (0)
; #define PG8_LDA(dst, b, h) do { _Pragma("unroll") for (int m = 0; m < 4; ++m) _Pragma("unroll") for (int k = 0; k < 2; ++k) dst[m][k] = *(const LAS bf16x8*)(lds + PG8_SA(b, h) + aoff + m * 2048 + k * 1024); } while (0)
; #define PG8_LDB(dst, b, h) do { _Pragma("unroll") for (int n = 0; n < 2; ++n) _Pragma("unroll") for (int k = 0; k < 2; ++k) dst[n][k] = *(const LAS bf16x8*)(lds + PG8_SB(b, h) + boff + n * 2048 + k * 1024); } while (0)
; #define PG8_MMA(ai, bj, At, Bt) do { __builtin_amdgcn_s_setprio(1); _Pragma("unroll") for (int m = 0; m < 4; ++m) _Pragma("unroll") for (int n = 0; n < 2; ++n) _Pragma("unroll") for (int k = 0; k < 2; ++k) \
;         acc[ai][bj][m][n] = __builtin_amdgcn_mfma_f32_16x16x32_bf16(Bt[n][k], At[m][k], acc[ai][bj][m][n], 0, 0, 0); __builtin_amdgcn_s_setprio(0); } while (0)
; #define PG8_WAIT_V(n) asm volatile("s_waitcnt vmcnt(" #n ")" ::: "memory")
; #define PG8_WAIT_L(n) asm volatile("s_waitcnt lgkmcnt(" #n ")" ::: "memory")
; #define PG8_BAR __builtin_amdgcn_s_barrier()
; #define PG8_SCHED __builtin_amdgcn_sched_barrier(0)
; template <class Epi>
; DI void gemm_phase(LAS unsigned char* lds, const Gemm g, const StaticOrder& S, const Epi& E) {
;     ...
;             PG8_LDB(B0, 0, 0); PG8_LDB(B1, 0, 1); PG8_SCHED; PG8_LDA(At, 0, 0); PG8_STAGE(PG8_SA(1, 1), a1 + hstep, voffA);
;             PG8_WAIT_V(8); PG8_WAIT_L(0); PG8_BAR; PG8_MMA(0, 0, At, B0); PG8_MMA(0, 1, At, B1); PG8_BAR; PG8_SCHED;
;             PG8_LDA(At, 0, 1); PG8_STAGE(PG8_SB(0, 0), b2, voffB); PG8_STAGE(PG8_SB(0, 1), b2 + hstep, voffB); PG8_STAGE(PG8_SA(0, 0), a2, voffA);
;             PG8_WAIT_V(8); PG8_WAIT_L(0); PG8_BAR; PG8_MMA(1, 0, At, B0); PG8_MMA(1, 1, At, B1); PG8_BAR; PG8_SCHED;
.LBB0_701:
	s_add_u32 s18, s56, 0xfffc0080
	s_addc_u32 s19, s57, -1
	s_add_i32 s69, 0, 0x10000
	s_cmp_eq_u32 s68, 12
	s_cselect_b32 s61, s22, s19
	s_cselect_b32 s60, s23, s18
	v_add_u32_e32 v122, s69, v184
	s_cselect_b32 s59, s42, s49
	s_cselect_b32 s58, s43, s47
	s_add_i32 s70, 0, 0x14000
	ds_read_b128 v[102:105], v122
	ds_read_b128 v[132:135], v122 offset:1024
	ds_read_b128 v[140:143], v122 offset:2048
	ds_read_b128 v[144:147], v122 offset:3072
	v_add_u32_e32 v122, s70, v184
	ds_read_b128 v[148:151], v122
	ds_read_b128 v[166:169], v122 offset:1024
	ds_read_b128 v[170:173], v122 offset:2048
	ds_read_b128 v[174:177], v122 offset:3072
	s_add_i32 m0, s55, 0xc000
	ds_read_b128 v[178:181], v186
	ds_read_b128 v[188:191], v186 offset:1024
	ds_read_b128 v[200:203], v186 offset:2048
	ds_read_b128 v[206:209], v186 offset:3072
	ds_read_b128 v[210:213], v186 offset:4096
	ds_read_b128 v[214:217], v186 offset:5120
	ds_read_b128 v[218:221], v186 offset:6144
	ds_read_b128 v[222:225], v186 offset:7168
	global_load_lds_dwordx4 v164, s[56:57]
	s_add_i32 m0, s55, 0xe000
	s_nop 0
	global_load_lds_dwordx4 v162, s[56:57]
	s_waitcnt vmcnt(8)
	s_waitcnt lgkmcnt(0)
	s_barrier
	s_waitcnt lgkmcnt(0)
	v_mfma_f32_16x16x32_bf16 v[136:139], v[102:105], v[178:181], v[136:139]
	v_mfma_f32_16x16x32_bf16 v[128:131], v[140:143], v[178:181], v[128:131]
	v_mfma_f32_16x16x32_bf16 v[118:121], v[102:105], v[200:203], v[118:121]
	v_mfma_f32_16x16x32_bf16 v[110:113], v[140:143], v[200:203], v[110:113]
	v_mfma_f32_16x16x32_bf16 v[98:101], v[102:105], v[210:213], v[98:101]
	v_mfma_f32_16x16x32_bf16 v[90:93], v[140:143], v[210:213], v[90:93]
	v_mfma_f32_16x16x32_bf16 v[78:81], v[102:105], v[218:221], v[78:81]
	v_mfma_f32_16x16x32_bf16 v[70:73], v[140:143], v[218:221], v[70:73]
	v_mfma_f32_16x16x32_bf16 v[136:139], v[132:135], v[188:191], v[136:139]
	v_mfma_f32_16x16x32_bf16 v[128:131], v[144:147], v[188:191], v[128:131]
	v_mfma_f32_16x16x32_bf16 v[118:121], v[132:135], v[206:209], v[118:121]
	v_mfma_f32_16x16x32_bf16 v[110:113], v[144:147], v[206:209], v[110:113]
	v_mfma_f32_16x16x32_bf16 v[98:101], v[132:135], v[214:217], v[98:101]
	v_mfma_f32_16x16x32_bf16 v[90:93], v[144:147], v[214:217], v[90:93]
	v_mfma_f32_16x16x32_bf16 v[78:81], v[132:135], v[222:225], v[78:81]
	v_mfma_f32_16x16x32_bf16 v[70:73], v[144:147], v[222:225], v[70:73]
	v_mfma_f32_16x16x32_bf16 v[82:85], v[148:151], v[178:181], v[82:85]
	v_mfma_f32_16x16x32_bf16 v[122:125], v[170:173], v[178:181], v[124:127]
	v_mfma_f32_16x16x32_bf16 v[114:117], v[148:151], v[200:203], v[114:117]
	v_mfma_f32_16x16x32_bf16 v[106:109], v[170:173], v[200:203], v[106:109]
	v_mfma_f32_16x16x32_bf16 v[94:97], v[148:151], v[210:213], v[94:97]
	v_mfma_f32_16x16x32_bf16 v[86:89], v[170:173], v[210:213], v[86:89]
	v_mfma_f32_16x16x32_bf16 v[74:77], v[148:151], v[218:221], v[74:77]
	v_mfma_f32_16x16x32_bf16 v[66:69], v[170:173], v[218:221], v[66:69]
	v_mfma_f32_16x16x32_bf16 v[82:85], v[166:169], v[188:191], v[82:85]
	v_mfma_f32_16x16x32_bf16 v[122:125], v[174:177], v[188:191], v[122:125]
	v_mfma_f32_16x16x32_bf16 v[114:117], v[166:169], v[206:209], v[114:117]
	v_mfma_f32_16x16x32_bf16 v[106:109], v[174:177], v[206:209], v[106:109]
	v_mfma_f32_16x16x32_bf16 v[94:97], v[166:169], v[214:217], v[94:97]
	v_mfma_f32_16x16x32_bf16 v[86:89], v[174:177], v[214:217], v[86:89]
	v_mfma_f32_16x16x32_bf16 v[74:77], v[166:169], v[222:225], v[74:77]
	v_mfma_f32_16x16x32_bf16 v[66:69], v[174:177], v[222:225], v[66:69]
	s_barrier
	s_add_i32 s18, s69, s37
	v_lshl_add_u64 v[182:183], s[58:59], 0, v[156:157]
	s_mov_b32 m0, s18
	ds_read_b128 v[178:181], v186 offset:16384
	ds_read_b128 v[188:191], v186 offset:17408
	ds_read_b128 v[200:203], v186 offset:18432
	ds_read_b128 v[206:209], v186 offset:19456
	ds_read_b128 v[210:213], v186 offset:20480
	ds_read_b128 v[214:217], v186 offset:21504
	ds_read_b128 v[218:221], v186 offset:22528
	ds_read_b128 v[222:225], v186 offset:23552
	global_load_lds_dwordx4 v[182:183], off
	s_add_i32 m0, s18, 0x2000
	s_add_u32 s18, s58, 0x40000
	v_lshl_add_u64 v[192:193], s[58:59], 0, v[152:153]
	s_addc_u32 s19, s59, 0
	s_add_i32 s69, s70, s37
	global_load_lds_dwordx4 v[192:193], off
	s_mov_b32 m0, s69
	v_lshl_add_u64 v[204:205], s[60:61], 0, v[158:159]
	global_load_lds_dwordx4 v156, s[18:19]
	s_add_i32 m0, s69, 0x2000
	v_lshl_add_u64 v[226:227], s[60:61], 0, v[154:155]
	global_load_lds_dwordx4 v152, s[18:19]
	s_mov_b32 m0, s55
	s_nop 0
	global_load_lds_dwordx4 v[204:205], off
	s_mov_b32 m0, s63
	s_nop 0
	global_load_lds_dwordx4 v[226:227], off
	s_waitcnt vmcnt(8)
	s_waitcnt lgkmcnt(0)
	s_barrier
	s_waitcnt lgkmcnt(0)
	v_mfma_f32_16x16x32_bf16 v[62:65], v[102:105], v[178:181], v[62:65]
	v_mfma_f32_16x16x32_bf16 v[54:57], v[140:143], v[178:181], v[54:57]
	v_mfma_f32_16x16x32_bf16 v[46:49], v[102:105], v[200:203], v[46:49]
	v_mfma_f32_16x16x32_bf16 v[38:41], v[140:143], v[200:203], v[38:41]
	v_mfma_f32_16x16x32_bf16 v[30:33], v[102:105], v[210:213], v[30:33]
	v_mfma_f32_16x16x32_bf16 v[22:25], v[140:143], v[210:213], v[22:25]
	v_mfma_f32_16x16x32_bf16 v[14:17], v[102:105], v[218:221], v[14:17]
	v_mfma_f32_16x16x32_bf16 v[6:9], v[140:143], v[218:221], v[6:9]
	v_mfma_f32_16x16x32_bf16 v[62:65], v[132:135], v[188:191], v[62:65]
	v_mfma_f32_16x16x32_bf16 v[54:57], v[144:147], v[188:191], v[54:57]
	v_mfma_f32_16x16x32_bf16 v[46:49], v[132:135], v[206:209], v[46:49]
	v_mfma_f32_16x16x32_bf16 v[38:41], v[144:147], v[206:209], v[38:41]
	v_mfma_f32_16x16x32_bf16 v[30:33], v[132:135], v[214:217], v[30:33]
	v_mfma_f32_16x16x32_bf16 v[22:25], v[144:147], v[214:217], v[22:25]
	v_mfma_f32_16x16x32_bf16 v[14:17], v[132:135], v[222:225], v[14:17]
	v_mfma_f32_16x16x32_bf16 v[6:9], v[144:147], v[222:225], v[6:9]
	v_mfma_f32_16x16x32_bf16 v[58:61], v[148:151], v[178:181], v[58:61]
	v_mfma_f32_16x16x32_bf16 v[50:53], v[170:173], v[178:181], v[50:53]
	v_mfma_f32_16x16x32_bf16 v[42:45], v[148:151], v[200:203], v[42:45]
	v_mfma_f32_16x16x32_bf16 v[34:37], v[170:173], v[200:203], v[34:37]
	v_mfma_f32_16x16x32_bf16 v[26:29], v[148:151], v[210:213], v[26:29]
	v_mfma_f32_16x16x32_bf16 v[18:21], v[170:173], v[210:213], v[18:21]
	v_mfma_f32_16x16x32_bf16 v[10:13], v[148:151], v[218:221], v[10:13]
	v_mfma_f32_16x16x32_bf16 v[2:5], v[170:173], v[218:221], v[2:5]
	v_mfma_f32_16x16x32_bf16 v[58:61], v[166:169], v[188:191], v[58:61]
	v_mfma_f32_16x16x32_bf16 v[50:53], v[174:177], v[188:191], v[50:53]
	v_mfma_f32_16x16x32_bf16 v[42:45], v[166:169], v[206:209], v[42:45]
	v_mfma_f32_16x16x32_bf16 v[34:37], v[174:177], v[206:209], v[34:37]
	v_mfma_f32_16x16x32_bf16 v[26:29], v[166:169], v[214:217], v[26:29]
	v_mfma_f32_16x16x32_bf16 v[18:21], v[174:177], v[214:217], v[18:21]
	v_mfma_f32_16x16x32_bf16 v[10:13], v[166:169], v[222:225], v[10:13]
	v_mfma_f32_16x16x32_bf16 v[2:5], v[174:177], v[222:225], v[2:5]
	s_barrier
; #define PG8_STAGE(bufoff, gbase, voff) do { _Pragma("unroll") for (int _i = 0; _i < 2; ++_i) \
;         __builtin_amdgcn_global_load_lds((const unsigned*)((const char*)(gbase) + (voff)[_i]), (LAS unsigned*)(lds + (bufoff) + ldsw + _i * 8192), 16, 0, 0); } while (0)
; #define PG8_LDA(dst, b, h) do { _Pragma("unroll") for (int m = 0; m < 4; ++m) _Pragma("unroll") for (int k = 0; k < 2; ++k) dst[m][k] = *(const LAS bf16x8*)(lds + PG8_SA(b, h) + aoff + m * 2048 + k * 1024); } while (0)
; #define PG8_LDB(dst, b, h) do { _Pragma("unroll") for (int n = 0; n < 2; ++n) _Pragma("unroll") for (int k = 0; k < 2; ++k) dst[n][k] = *(const LAS bf16x8*)(lds + PG8_SB(b, h) + boff + n * 2048 + k * 1024); } while (0)
; #define PG8_MMA(ai, bj, At, Bt) do { __builtin_amdgcn_s_setprio(1); _Pragma("unroll") for (int m = 0; m < 4; ++m) _Pragma("unroll") for (int n = 0; n < 2; ++n) _Pragma("unroll") for (int k = 0; k < 2; ++k) \
;         acc[ai][bj][m][n] = __builtin_amdgcn_mfma_f32_16x16x32_bf16(Bt[n][k], At[m][k], acc[ai][bj][m][n], 0, 0, 0); __builtin_amdgcn_s_setprio(0); } while (0)
; #define PG8_WAIT_V(n) asm volatile("s_waitcnt vmcnt(" #n ")" ::: "memory")
; #define PG8_WAIT_L(n) asm volatile("s_waitcnt lgkmcnt(" #n ")" ::: "memory")
; #define PG8_BAR __builtin_amdgcn_s_barrier()
; #define PG8_SCHED __builtin_amdgcn_sched_barrier(0)
; template <class Epi>
; DI void gemm_phase(LAS unsigned char* lds, const Gemm g, const StaticOrder& S, const Epi& E) {
;     ...
;             PG8_LDB(B0, 1, 0); PG8_LDB(B1, 1, 1); PG8_SCHED; PG8_LDA(At, 1, 0); PG8_STAGE(PG8_SA(0, 1), a2 + hstep, voffA);
;             PG8_WAIT_V(8); PG8_WAIT_L(0); PG8_BAR; PG8_MMA(0, 0, At, B0); PG8_MMA(0, 1, At, B1); PG8_BAR; PG8_SCHED;
;             PG8_LDA(At, 1, 1); PG8_STAGE(PG8_SB(1, 0), b3, voffB); PG8_STAGE(PG8_SB(1, 1), b3 + hstep, voffB); PG8_STAGE(PG8_SA(1, 0), a3, voffA);
;             PG8_WAIT_V(8); PG8_WAIT_L(0); PG8_BAR; PG8_MMA(1, 0, At, B0); PG8_MMA(1, 1, At, B1); PG8_BAR; PG8_SCHED;
;         }
.Lp3_gu:
	s_add_i32 s69, 0, 0x18000
	v_add_u32_e32 v126, s69, v184
	s_add_i32 s70, 0, 0x1c000
	ds_read_b128 v[102:105], v126
	ds_read_b128 v[132:135], v126 offset:1024
	ds_read_b128 v[140:143], v126 offset:2048
	ds_read_b128 v[144:147], v126 offset:3072
	v_add_u32_e32 v126, s70, v184
	ds_read_b128 v[148:151], v126
	ds_read_b128 v[166:169], v126 offset:1024
	ds_read_b128 v[170:173], v126 offset:2048
	ds_read_b128 v[174:177], v126 offset:3072
	s_add_u32 s18, s60, 0x40000
	s_addc_u32 s19, s61, 0
	s_mov_b32 m0, s64
	ds_read_b128 v[178:181], v186 offset:32768
	ds_read_b128 v[188:191], v186 offset:33792
	ds_read_b128 v[200:203], v186 offset:34816
	ds_read_b128 v[206:209], v186 offset:35840
	ds_read_b128 v[210:213], v186 offset:36864
	ds_read_b128 v[214:217], v186 offset:37888
	ds_read_b128 v[218:221], v186 offset:38912
	ds_read_b128 v[222:225], v186 offset:39936
	global_load_lds_dwordx4 v158, s[18:19]
	s_mov_b32 m0, s65
	s_nop 0
	global_load_lds_dwordx4 v154, s[18:19]
	s_waitcnt vmcnt(8)
	s_waitcnt lgkmcnt(0)
	s_barrier
	s_waitcnt lgkmcnt(0)
	v_mfma_f32_16x16x32_bf16 v[136:139], v[102:105], v[178:181], v[136:139]
	v_mfma_f32_16x16x32_bf16 v[126:129], v[140:143], v[178:181], v[128:131]
	v_mfma_f32_16x16x32_bf16 v[118:121], v[102:105], v[200:203], v[118:121]
	v_mfma_f32_16x16x32_bf16 v[110:113], v[140:143], v[200:203], v[110:113]
	v_mfma_f32_16x16x32_bf16 v[98:101], v[102:105], v[210:213], v[98:101]
	v_mfma_f32_16x16x32_bf16 v[90:93], v[140:143], v[210:213], v[90:93]
	v_mfma_f32_16x16x32_bf16 v[78:81], v[102:105], v[218:221], v[78:81]
	v_mfma_f32_16x16x32_bf16 v[70:73], v[140:143], v[218:221], v[70:73]
	v_mfma_f32_16x16x32_bf16 v[136:139], v[132:135], v[188:191], v[136:139]
	v_mfma_f32_16x16x32_bf16 v[128:131], v[144:147], v[188:191], v[126:129]
	v_mfma_f32_16x16x32_bf16 v[118:121], v[132:135], v[206:209], v[118:121]
	v_mfma_f32_16x16x32_bf16 v[110:113], v[144:147], v[206:209], v[110:113]
	v_mfma_f32_16x16x32_bf16 v[98:101], v[132:135], v[214:217], v[98:101]
	v_mfma_f32_16x16x32_bf16 v[90:93], v[144:147], v[214:217], v[90:93]
	v_mfma_f32_16x16x32_bf16 v[78:81], v[132:135], v[222:225], v[78:81]
	v_mfma_f32_16x16x32_bf16 v[70:73], v[144:147], v[222:225], v[70:73]
	v_mfma_f32_16x16x32_bf16 v[82:85], v[148:151], v[178:181], v[82:85]
	v_mfma_f32_16x16x32_bf16 v[122:125], v[170:173], v[178:181], v[122:125]
	v_mfma_f32_16x16x32_bf16 v[114:117], v[148:151], v[200:203], v[114:117]
	v_mfma_f32_16x16x32_bf16 v[106:109], v[170:173], v[200:203], v[106:109]
	v_mfma_f32_16x16x32_bf16 v[94:97], v[148:151], v[210:213], v[94:97]
	v_mfma_f32_16x16x32_bf16 v[86:89], v[170:173], v[210:213], v[86:89]
	v_mfma_f32_16x16x32_bf16 v[74:77], v[148:151], v[218:221], v[74:77]
	v_mfma_f32_16x16x32_bf16 v[66:69], v[170:173], v[218:221], v[66:69]
	v_mfma_f32_16x16x32_bf16 v[82:85], v[166:169], v[188:191], v[82:85]
	v_mfma_f32_16x16x32_bf16 v[124:127], v[174:177], v[188:191], v[122:125]
	v_mfma_f32_16x16x32_bf16 v[114:117], v[166:169], v[206:209], v[114:117]
	v_mfma_f32_16x16x32_bf16 v[106:109], v[174:177], v[206:209], v[106:109]
	v_mfma_f32_16x16x32_bf16 v[94:97], v[166:169], v[214:217], v[94:97]
	v_mfma_f32_16x16x32_bf16 v[86:89], v[174:177], v[214:217], v[86:89]
	v_mfma_f32_16x16x32_bf16 v[74:77], v[166:169], v[222:225], v[74:77]
	v_mfma_f32_16x16x32_bf16 v[66:69], v[174:177], v[222:225], v[66:69]
	s_barrier
	s_add_i32 s18, s69, s37
	v_lshl_add_u64 v[122:123], v[182:183], 0, s[20:21]
	s_mov_b32 m0, s18
	ds_read_b128 v[178:181], v186 offset:49152
	ds_read_b128 v[188:191], v186 offset:50176
	ds_read_b128 v[200:203], v186 offset:51200
	ds_read_b128 v[206:209], v186 offset:52224
	ds_read_b128 v[210:213], v186 offset:53248
	ds_read_b128 v[214:217], v186 offset:54272
	ds_read_b128 v[218:221], v186 offset:55296
	ds_read_b128 v[222:225], v186 offset:56320
	global_load_lds_dwordx4 v[122:123], off
	s_add_i32 m0, s18, 0x2000
	s_add_u32 s18, s58, 0x40080
	v_lshl_add_u64 v[122:123], v[192:193], 0, s[20:21]
	s_addc_u32 s19, s59, 0
	s_add_i32 s58, s70, s37
	global_load_lds_dwordx4 v[122:123], off
	s_mov_b32 m0, s58
	s_nop 0
	global_load_lds_dwordx4 v156, s[18:19]
	s_add_i32 m0, s58, 0x2000
	s_nop 0
	global_load_lds_dwordx4 v152, s[18:19]
	v_lshl_add_u64 v[122:123], v[204:205], 0, s[20:21]
	s_mov_b32 m0, s66
	s_nop 0
	global_load_lds_dwordx4 v[122:123], off
	v_lshl_add_u64 v[122:123], v[226:227], 0, s[20:21]
	s_mov_b32 m0, s67
	s_nop 0
	global_load_lds_dwordx4 v[122:123], off
	s_waitcnt vmcnt(8)
	s_waitcnt lgkmcnt(0)
	s_barrier
	s_waitcnt lgkmcnt(0)
	v_mfma_f32_16x16x32_bf16 v[62:65], v[102:105], v[178:181], v[62:65]
	v_mfma_f32_16x16x32_bf16 v[54:57], v[140:143], v[178:181], v[54:57]
	v_mfma_f32_16x16x32_bf16 v[46:49], v[102:105], v[200:203], v[46:49]
	v_mfma_f32_16x16x32_bf16 v[38:41], v[140:143], v[200:203], v[38:41]
	v_mfma_f32_16x16x32_bf16 v[30:33], v[102:105], v[210:213], v[30:33]
	v_mfma_f32_16x16x32_bf16 v[22:25], v[140:143], v[210:213], v[22:25]
	v_mfma_f32_16x16x32_bf16 v[14:17], v[102:105], v[218:221], v[14:17]
	v_mfma_f32_16x16x32_bf16 v[6:9], v[140:143], v[218:221], v[6:9]
	v_mfma_f32_16x16x32_bf16 v[62:65], v[132:135], v[188:191], v[62:65]
	v_mfma_f32_16x16x32_bf16 v[54:57], v[144:147], v[188:191], v[54:57]
	v_mfma_f32_16x16x32_bf16 v[46:49], v[132:135], v[206:209], v[46:49]
	v_mfma_f32_16x16x32_bf16 v[38:41], v[144:147], v[206:209], v[38:41]
	v_mfma_f32_16x16x32_bf16 v[30:33], v[132:135], v[214:217], v[30:33]
	v_mfma_f32_16x16x32_bf16 v[22:25], v[144:147], v[214:217], v[22:25]
	v_mfma_f32_16x16x32_bf16 v[14:17], v[132:135], v[222:225], v[14:17]
	v_mfma_f32_16x16x32_bf16 v[6:9], v[144:147], v[222:225], v[6:9]
	v_mfma_f32_16x16x32_bf16 v[58:61], v[148:151], v[178:181], v[58:61]
	v_mfma_f32_16x16x32_bf16 v[50:53], v[170:173], v[178:181], v[50:53]
	v_mfma_f32_16x16x32_bf16 v[42:45], v[148:151], v[200:203], v[42:45]
	v_mfma_f32_16x16x32_bf16 v[34:37], v[170:173], v[200:203], v[34:37]
	v_mfma_f32_16x16x32_bf16 v[26:29], v[148:151], v[210:213], v[26:29]
	v_mfma_f32_16x16x32_bf16 v[18:21], v[170:173], v[210:213], v[18:21]
	v_mfma_f32_16x16x32_bf16 v[10:13], v[148:151], v[218:221], v[10:13]
	v_mfma_f32_16x16x32_bf16 v[2:5], v[170:173], v[218:221], v[2:5]
	v_mfma_f32_16x16x32_bf16 v[58:61], v[166:169], v[188:191], v[58:61]
	v_mfma_f32_16x16x32_bf16 v[50:53], v[174:177], v[188:191], v[50:53]
	v_mfma_f32_16x16x32_bf16 v[42:45], v[166:169], v[206:209], v[42:45]
	v_mfma_f32_16x16x32_bf16 v[34:37], v[174:177], v[206:209], v[34:37]
	v_mfma_f32_16x16x32_bf16 v[26:29], v[166:169], v[214:217], v[26:29]
	v_mfma_f32_16x16x32_bf16 v[18:21], v[174:177], v[214:217], v[18:21]
	v_mfma_f32_16x16x32_bf16 v[10:13], v[166:169], v[222:225], v[10:13]
	v_mfma_f32_16x16x32_bf16 v[2:5], v[174:177], v[222:225], v[2:5]
	s_barrier
	s_add_i32 s68, s68, 2
	s_add_u32 s47, s47, 0x100
	s_addc_u32 s49, s49, 0
	s_add_u32 s56, s56, 0x100
	s_addc_u32 s57, s57, 0
	s_cmp_gt_u32 s68, 13
	s_cbranch_scc0 .LBB0_701
	s_setprio 0
	s_and_b64 vcc, exec, s[44:45]
	s_cbranch_vccz .LBB0_704
	s_barrier
